# queue pop: atomic issued before the pre-pop barrier (overlaps atomic round trip with barrier wait), on top of static first item
# speedup vs baseline: 1.0085x; 1.0001x over previous
; __global__ void __launch_bounds__(512) mega_fwd(Params P) {
;     ...
;             for (;;) {
;                 __syncthreads();
;                 if (tid == 0) *s_item = (int)atomicAdd(ctr, 1u);
;                 __syncthreads();
;                 const int it = *s_item;
.LBB0_1070:
	s_and_saveexec_b64 s[4:5], s[2:3]
	s_cbranch_execz .La1_pop_b
	v_mov_b64_e32 v[2:3], s[0:1]
	flat_atomic_add v0, v[2:3], v157 offset:256 sc0
.La1_pop_b:
	s_barrier
	s_cbranch_execz .LBB0_1072
	v_mov_b32_e32 v2, s16
	s_waitcnt vmcnt(0) lgkmcnt(0)
	ds_write_b32 v2, v0

; __global__ void __launch_bounds__(512) mega_fwd(Params P) {
;     ...
;             for (;;) {
;                 __syncthreads();
;                 if (tid == 0) *s_item = (int)atomicAdd(ctr, 1u);
;                 __syncthreads();
;                 const int it = *s_item;
.LBB0_1304:
	s_and_saveexec_b64 s[0:1], s[2:3]
	s_cbranch_execz .La3_pop_b
	v_mov_b64_e32 v[2:3], s[12:13]
	flat_atomic_add v0, v[2:3], v157 offset:512 sc0
.La3_pop_b:
	s_barrier
	s_cbranch_execz .LBB0_1306
	v_mov_b32_e32 v2, s38
	s_waitcnt vmcnt(0) lgkmcnt(0)
	ds_write_b32 v2, v0
